# barrier spin loops keep two polls of the flag word in flight (a new one issued as each returns, no sleep), halving the sampling period
# speedup vs baseline: 1.0006x; 1.0005x over previous
.LBB0_124:
	s_or_b64 exec, exec, s[4:5]
	s_waitcnt vmcnt(0)
	s_barrier
	s_mov_b64 s[4:5], exec
	v_readlane_b32 s0, v219, 25
	v_readlane_b32 s1, v219, 26
	s_and_b64 s[0:1], s[4:5], s[0:1]
	s_mov_b64 exec, s[0:1]
	s_cbranch_execz .LBB0_176
	v_readlane_b32 s0, v219, 27
	v_readlane_b32 s1, v219, 28
	v_readlane_b32 s2, v219, 30
	s_waitcnt vmcnt(0) lgkmcnt(0)
	buffer_inv sc1
	s_and_b32 s3, s2, 31
	s_lshl_b32 s3, s3, 7
	s_add_i32 s3, s3, 64
	v_mov_b32_e32 v1, s3
	v_mov_b32_e32 v0, 1
	s_nop 1
	global_atomic_add v1, v0, s[0:1]
	s_mov_b32 s15, 0
	global_load_dword v2, v1, s[0:1] sc1
.Lgb2_spin:
	global_load_dword v0, v1, s[0:1] sc1
	s_waitcnt vmcnt(1)
	v_readfirstlane_b32 s13, v2
	s_nop 1
	s_cmp_ge_u32 s13, 8
	s_cbranch_scc1 .Lgb2_done
	global_load_dword v2, v1, s[0:1] sc1
	s_waitcnt vmcnt(1)
	v_readfirstlane_b32 s13, v0
	s_nop 1
	s_cmp_ge_u32 s13, 8
	s_cbranch_scc1 .Lgb2_done
	s_add_i32 s15, s15, 1
	s_cmp_lt_u32 s15, 0x200000
	s_cbranch_scc1 .Lgb2_spin

.Lnb3_wait:
	v_mov_b32_e32 v1, s14
	s_mov_b32 s15, 0
	global_load_dword v2, v1, s[0:1] sc1
.Lnb3_spin:
	global_load_dword v0, v1, s[0:1] sc1
	s_waitcnt vmcnt(1)
	v_readfirstlane_b32 s13, v2
	s_nop 1
	s_cmp_ge_u32 s13, 2
	s_cbranch_scc1 .Lnb3_done
	global_load_dword v2, v1, s[0:1] sc1
	s_waitcnt vmcnt(1)
	v_readfirstlane_b32 s13, v0
	s_nop 1
	s_cmp_ge_u32 s13, 2
	s_cbranch_scc1 .Lnb3_done
	s_add_i32 s15, s15, 1
	s_cmp_lt_u32 s15, 0x200000
	s_cbranch_scc1 .Lnb3_spin

.Lnb4_spin:
	global_load_dword v0, v1, s[0:1] sc1
	s_waitcnt vmcnt(1)
	v_readfirstlane_b32 s13, v2
	s_nop 1
	s_cmp_ge_u32 s13, 3
	s_cbranch_scc1 .Lnb4_done
	global_load_dword v2, v1, s[0:1] sc1
	s_waitcnt vmcnt(1)
	v_readfirstlane_b32 s13, v0
	s_nop 1
	s_cmp_ge_u32 s13, 3
	s_cbranch_scc1 .Lnb4_done
	s_add_i32 s15, s15, 1
	s_cmp_lt_u32 s15, 0x200000
	s_cbranch_scc1 .Lnb4_spin

.LBB0_512:
	s_waitcnt vmcnt(0)
	s_waitcnt vmcnt(0) lgkmcnt(0)
	s_barrier
	s_mov_b64 s[4:5], exec
	v_readlane_b32 s0, v219, 25
	v_readlane_b32 s1, v219, 26
	s_and_b64 s[0:1], s[4:5], s[0:1]
	s_mov_b64 exec, s[0:1]
	s_cbranch_execz .LBB0_564
	v_readlane_b32 s0, v219, 27
	v_readlane_b32 s1, v219, 28
	v_readlane_b32 s2, v219, 30
	s_waitcnt vmcnt(0) lgkmcnt(0)
	buffer_inv sc1
	s_and_b32 s3, s2, 31
	s_lshl_b32 s3, s3, 7
	s_add_i32 s3, s3, 64
	v_mov_b32_e32 v1, s3
	v_mov_b32_e32 v0, 1
	s_nop 1
	global_atomic_add v1, v0, s[0:1]
	s_mov_b32 s15, 0
	global_load_dword v2, v1, s[0:1] sc1
.Lgb5_spin:
	global_load_dword v0, v1, s[0:1] sc1
	s_waitcnt vmcnt(1)
	v_readfirstlane_b32 s13, v2
	s_nop 1
	s_cmp_ge_u32 s13, 16
	s_cbranch_scc1 .Lgb5_done
	global_load_dword v2, v1, s[0:1] sc1
	s_waitcnt vmcnt(1)
	v_readfirstlane_b32 s13, v0
	s_nop 1
	s_cmp_ge_u32 s13, 16
	s_cbranch_scc1 .Lgb5_done
	s_add_i32 s15, s15, 1
	s_cmp_lt_u32 s15, 0x200000
	s_cbranch_scc1 .Lgb5_spin

.Lgb6_spin:
	global_load_dword v0, v1, s[0:1] sc1
	s_waitcnt vmcnt(1)
	v_readfirstlane_b32 s13, v2
	s_nop 1
	s_cmp_ge_u32 s13, 24
	s_cbranch_scc1 .Lgb6_done
	global_load_dword v2, v1, s[0:1] sc1
	s_waitcnt vmcnt(1)
	v_readfirstlane_b32 s13, v0
	s_nop 1
	s_cmp_ge_u32 s13, 24
	s_cbranch_scc1 .Lgb6_done
	s_add_i32 s15, s15, 1
	s_cmp_lt_u32 s15, 0x200000
	s_cbranch_scc1 .Lgb6_spin

.Lgb7_spin:
	global_load_dword v0, v1, s[0:1] sc1
	s_waitcnt vmcnt(1)
	v_readfirstlane_b32 s13, v2
	s_nop 1
	s_cmp_ge_u32 s13, 32
	s_cbranch_scc1 .Lgb7_done
	global_load_dword v2, v1, s[0:1] sc1
	s_waitcnt vmcnt(1)
	v_readfirstlane_b32 s13, v0
	s_nop 1
	s_cmp_ge_u32 s13, 32
	s_cbranch_scc1 .Lgb7_done
	s_add_i32 s15, s15, 1
	s_cmp_lt_u32 s15, 0x200000
	s_cbranch_scc1 .Lgb7_spin

.LBB0_809:
	s_waitcnt vmcnt(0)
	s_waitcnt vmcnt(0) lgkmcnt(0)
	s_barrier
	s_mov_b64 s[6:7], exec
	v_readlane_b32 s0, v219, 25
	v_readlane_b32 s1, v219, 26
	s_and_b64 s[0:1], s[6:7], s[0:1]
	s_mov_b64 exec, s[0:1]
	s_cbranch_execz .LBB0_861
	v_readlane_b32 s0, v219, 27
	v_readlane_b32 s1, v219, 28
	v_readlane_b32 s2, v219, 30
	s_waitcnt vmcnt(0) lgkmcnt(0)
	buffer_inv sc1
	s_and_b32 s3, s2, 31
	s_lshl_b32 s3, s3, 7
	s_add_i32 s3, s3, 64
	v_mov_b32_e32 v1, s3
	v_mov_b32_e32 v0, 1
	s_nop 1
	global_atomic_add v1, v0, s[0:1]
	v_mov_b32_e32 v2, 0x1040
	global_atomic_add v2, v0, s[0:1]
	s_mov_b32 s15, 0
	global_load_dword v2, v1, s[0:1] sc1
.Lgb8_spin:
	global_load_dword v0, v1, s[0:1] sc1
	s_waitcnt vmcnt(1)
	v_readfirstlane_b32 s13, v2
	s_nop 1
	s_cmp_ge_u32 s13, 40
	s_cbranch_scc1 .Lgb8_done
	global_load_dword v2, v1, s[0:1] sc1
	s_waitcnt vmcnt(1)
	v_readfirstlane_b32 s13, v0
	s_nop 1
	s_cmp_ge_u32 s13, 40
	s_cbranch_scc1 .Lgb8_done
	s_add_i32 s15, s15, 1
	s_cmp_lt_u32 s15, 0x200000
	s_cbranch_scc1 .Lgb8_spin

.LBB0_866:
	s_or_b64 exec, exec, s[6:7]
	s_waitcnt vmcnt(0)
	s_barrier
	s_mov_b64 s[6:7], exec
	v_readlane_b32 s0, v219, 25
	v_readlane_b32 s1, v219, 26
	s_and_b64 s[0:1], s[6:7], s[0:1]
	s_mov_b64 exec, s[0:1]
	s_cbranch_execz .LBB0_918
	v_readlane_b32 s0, v219, 27
	v_readlane_b32 s1, v219, 28
	v_readlane_b32 s2, v219, 30
	s_waitcnt vmcnt(0) lgkmcnt(0)
	buffer_inv sc1
	s_and_b32 s3, s2, 31
	s_lshl_b32 s3, s3, 7
	s_add_i32 s3, s3, 64
	v_mov_b32_e32 v1, s3
	v_mov_b32_e32 v0, 1
	s_nop 1
	global_atomic_add v1, v0, s[0:1]
	s_mov_b32 s15, 0
	global_load_dword v2, v1, s[0:1] sc1
.Lgb9_spin:
	global_load_dword v0, v1, s[0:1] sc1
	s_waitcnt vmcnt(1)
	v_readfirstlane_b32 s13, v2
	s_nop 1
	s_cmp_ge_u32 s13, 48
	s_cbranch_scc1 .Lgb9_done
	global_load_dword v2, v1, s[0:1] sc1
	s_waitcnt vmcnt(1)
	v_readfirstlane_b32 s13, v0
	s_nop 1
	s_cmp_ge_u32 s13, 48
	s_cbranch_scc1 .Lgb9_done
	s_add_i32 s15, s15, 1
	s_cmp_lt_u32 s15, 0x200000
	s_cbranch_scc1 .Lgb9_spin

.Lqb10_cw:
	v_mov_b32_e32 v1, s3
	s_mov_b32 s15, 0
	global_load_dword v2, v1, s[0:1] sc1

.LBB0_1120:
	s_waitcnt vmcnt(0)
	s_barrier
	s_mov_b64 s[6:7], exec
	v_readlane_b32 s0, v219, 25
	v_readlane_b32 s1, v219, 26
	s_and_b64 s[0:1], s[6:7], s[0:1]
	s_mov_b64 exec, s[0:1]
	s_cbranch_execz .LBB0_1172
	v_readlane_b32 s0, v219, 27
	v_readlane_b32 s1, v219, 28
	v_readlane_b32 s2, v219, 30
	s_waitcnt vmcnt(0) lgkmcnt(0)
	buffer_inv sc1
	s_bfe_u32 s3, s2, 0x10002
	s_lshl_b32 s3, s3, 3
	s_bfe_u32 s10, s2, 0x30004
	s_add_i32 s3, s3, s10
	s_add_i32 s3, s3, 16
	s_lshl_b32 s3, s3, 7
	s_add_i32 s3, s3, 0x60
	s_lshr_b32 s10, s2, 4
	s_lshl_b32 s10, s10, 7
	s_add_i32 s10, s10, 0x60
	s_and_b32 s11, s2, 31
	s_lshl_b32 s11, s11, 7
	s_add_i32 s11, s11, 0x60
	v_mov_b32_e32 v0, 1
	v_mov_b32_e32 v1, s3
	v_mov_b32_e32 v2, s10
	s_nop 1
	global_atomic_add v1, v0, s[0:1]
	global_atomic_add v2, v0, s[0:1]
	v_mov_b32_e32 v2, 0x1140
	s_nop 1
	global_atomic_add v2, v0, s[0:1]
	v_mov_b32_e32 v1, s11
	s_mov_b32 s15, 0
	global_load_dword v2, v1, s[0:1] sc1

.LBB0_1236:
	s_waitcnt vmcnt(0)
	s_waitcnt vmcnt(0) lgkmcnt(0)
	s_barrier
	s_mov_b64 s[6:7], exec
	v_readlane_b32 s0, v219, 25
	v_readlane_b32 s1, v219, 26
	s_and_b64 s[0:1], s[6:7], s[0:1]
	s_mov_b64 exec, s[0:1]
	s_cbranch_execz .LBB0_1288
	v_readlane_b32 s0, v219, 27
	v_readlane_b32 s1, v219, 28
	v_readlane_b32 s2, v219, 30
	s_waitcnt vmcnt(0) lgkmcnt(0)
	buffer_inv sc1
	s_and_b32 s3, s2, 31
	s_lshl_b32 s3, s3, 7
	s_add_i32 s3, s3, 64
	v_mov_b32_e32 v1, s3
	v_mov_b32_e32 v0, 1
	s_nop 1
	global_atomic_add v1, v0, s[0:1]
	s_mov_b32 s15, 0
	global_load_dword v2, v1, s[0:1] sc1
.Lgb12_spin:
	global_load_dword v0, v1, s[0:1] sc1
	s_waitcnt vmcnt(1)
	v_readfirstlane_b32 s13, v2
	s_nop 1
	s_cmp_ge_u32 s13, 56
	s_cbranch_scc1 .Lgb12_done
	global_load_dword v2, v1, s[0:1] sc1
	s_waitcnt vmcnt(1)
	v_readfirstlane_b32 s13, v0
	s_nop 1
	s_cmp_ge_u32 s13, 56
	s_cbranch_scc1 .Lgb12_done
	s_add_i32 s15, s15, 1
	s_cmp_lt_u32 s15, 0x200000
	s_cbranch_scc1 .Lgb12_spin

.Lgb13_spin:
	global_load_dword v0, v1, s[0:1] sc1
	s_waitcnt vmcnt(1)
	v_readfirstlane_b32 s13, v2
	s_nop 1
	s_cmp_ge_u32 s13, 64
	s_cbranch_scc1 .Lgb13_done
	global_load_dword v2, v1, s[0:1] sc1
	s_waitcnt vmcnt(1)
	v_readfirstlane_b32 s13, v0
	s_nop 1
	s_cmp_ge_u32 s13, 64
	s_cbranch_scc1 .Lgb13_done
	s_add_i32 s15, s15, 1
	s_cmp_lt_u32 s15, 0x200000
	s_cbranch_scc1 .Lgb13_spin

.Lgb14_spin:
	global_load_dword v0, v1, s[0:1] sc1
	s_waitcnt vmcnt(1)
	v_readfirstlane_b32 s13, v2
	s_nop 1
	s_cmp_ge_u32 s13, 72
	s_cbranch_scc1 .Lgb14_done
	global_load_dword v2, v1, s[0:1] sc1
	s_waitcnt vmcnt(1)
	v_readfirstlane_b32 s13, v0
	s_nop 1
	s_cmp_ge_u32 s13, 72
	s_cbranch_scc1 .Lgb14_done
	s_add_i32 s15, s15, 1
	s_cmp_lt_u32 s15, 0x200000
	s_cbranch_scc1 .Lgb14_spin

.Lgb15_spin:
	global_load_dword v0, v1, s[0:1] sc1
	s_waitcnt vmcnt(1)
	v_readfirstlane_b32 s13, v2
	s_nop 1
	s_cmp_ge_u32 s13, 80
	s_cbranch_scc1 .Lgb15_done
	global_load_dword v2, v1, s[0:1] sc1
	s_waitcnt vmcnt(1)
	v_readfirstlane_b32 s13, v0
	s_nop 1
	s_cmp_ge_u32 s13, 80
	s_cbranch_scc1 .Lgb15_done
	s_add_i32 s15, s15, 1
	s_cmp_lt_u32 s15, 0x200000
	s_cbranch_scc1 .Lgb15_spin
